# P5 out-proj k-loop: saddr LDS-DMA, interleaved, half-line stage pairs
# speedup vs baseline: 1.0800x; 1.0096x over previous
.LBB0_994:
	s_ashr_i32 s37, s36, 31
	s_lshr_b32 s37, s37, 26
	s_add_i32 s37, s36, s37
	s_andn2_b32 s37, s37, 63
	v_readlane_b32 s12, v254, 14
	s_add_i32 s46, s37, s12
	s_and_b32 s47, s36, 7
	s_sub_i32 s38, s36, s37
	s_or_b32 s36, s46, s47
	s_lshl_b32 s36, s36, 8
	s_lshl_b32 s37, s38, 4
	s_and_b32 s38, s37, 0xffffff80
	s_ashr_i32 s37, s36, 31
	v_mov_b32_e32 v16, v199
	s_lshl_b64 s[40:41], s[36:37], 11
	s_add_u32 s98, s68, s40
	s_addc_u32 s99, s69, s41
	s_ashr_i32 s39, s38, 31
	s_lshl_b64 s[40:41], s[38:39], 11
	s_add_u32 s100, s30, s40
	s_addc_u32 s101, s48, s41
	v_ashrrev_i32_e32 v2, 2, v16
	v_lshrrev_b32_e32 v17, 4, v16
	v_xor_b32_e32 v6, v17, v16
	v_lshlrev_b32_e32 v6, 4, v6
	v_and_b32_e32 v6, 48, v6
	v_lshl_add_u32 v187, v16, 4, 0
	v_lshl_or_b32 v224, v2, 11, v6
	v_add_u32_e32 v225, 0x20000, v224
	v_add_u32_e32 v226, 0x40000, v224
	v_add_u32_e32 v227, 0x60000, v224
	v_lshrrev_b32_e32 v8, 5, v16
	v_bfe_u32 v9, v16, 5, 1
	v_readfirstlane_b32 s50, v187
	v_bfe_u32 v10, v16, 2, 2
	v_bitop3_b32 v19, v8, v10, 1 bitop3:0x6c
	v_bitop3_b32 v20, v9, v10, 2 bitop3:0x36
	v_lshlrev_b32_e32 v18, 6, v16
	v_and_b32_e32 v188, 0xffffe7c0, v18
	v_lshl_add_u32 v189, v19, 4, 0
	v_and_b32_e32 v0, 0x17c0, v18
	v_lshl_add_u32 v190, v20, 4, 0
	s_add_u32 s40, s98, 64
	s_addc_u32 s41, s99, 0
	s_add_u32 s12, s100, 64
	s_addc_u32 s13, s101, 0
	s_barrier
	s_add_u32 m0, s50, 0x0
	v_mov_b32_e32 v2, 0
	global_load_lds_dwordx4 v224, s[98:99]
	s_add_u32 m0, s50, 0x6000
	v_mov_b32_e32 v3, 0
	global_load_lds_dwordx4 v224, s[40:41]
	s_add_u32 m0, s50, 0x1000
	v_mov_b32_e32 v4, 0
	global_load_lds_dwordx4 v225, s[98:99]
	s_add_u32 m0, s50, 0x7000
	v_mov_b32_e32 v5, 0
	global_load_lds_dwordx4 v225, s[40:41]
	s_add_u32 m0, s50, 0x2000
	v_mov_b32_e32 v6, 0
	global_load_lds_dwordx4 v226, s[98:99]
	s_add_u32 m0, s50, 0x8000
	v_mov_b32_e32 v7, 0
	global_load_lds_dwordx4 v226, s[40:41]
	s_add_u32 m0, s50, 0x3000
	v_mov_b32_e32 v8, 0
	global_load_lds_dwordx4 v227, s[98:99]
	s_add_u32 m0, s50, 0x9000
	v_mov_b32_e32 v9, 0
	global_load_lds_dwordx4 v227, s[40:41]
	s_add_u32 m0, s50, 0x4000
	v_mov_b32_e32 v10, 0
	global_load_lds_dwordx4 v224, s[100:101]
	s_add_u32 m0, s50, 0xa000
	v_mov_b32_e32 v11, 0
	global_load_lds_dwordx4 v224, s[12:13]
	s_add_u32 m0, s50, 0x5000
	v_mov_b32_e32 v12, 0
	global_load_lds_dwordx4 v225, s[100:101]
	s_add_u32 m0, s50, 0xb000
	v_mov_b32_e32 v13, 0
	global_load_lds_dwordx4 v225, s[12:13]
	s_add_u32 s98, s98, 0x80
	s_addc_u32 s99, s99, 0
	s_add_u32 s100, s100, 0x80
	s_addc_u32 s101, s101, 0
	s_add_u32 s40, s40, 0x80
	s_addc_u32 s41, s41, 0
	s_add_u32 s12, s12, 0x80
	s_addc_u32 s13, s13, 0
	v_mov_b32_e32 v14, 0
	v_mov_b32_e32 v15, 0
	v_mov_b32_e32 v16, 0
	v_mov_b32_e32 v17, 0
	v_mov_b32_e32 v18, 0
	v_mov_b32_e32 v19, 0
	v_mov_b32_e32 v20, 0
	v_mov_b32_e32 v21, 0
	v_mov_b32_e32 v22, 0
	v_mov_b32_e32 v23, 0
	v_mov_b32_e32 v24, 0
	v_mov_b32_e32 v25, 0
	v_mov_b32_e32 v26, 0
	v_mov_b32_e32 v27, 0
	v_mov_b32_e32 v28, 0
	v_mov_b32_e32 v29, 0
	v_mov_b32_e32 v30, 0
	v_mov_b32_e32 v31, 0
	v_mov_b32_e32 v32, 0
	v_mov_b32_e32 v33, 0
	v_mov_b32_e32 v34, 0
	v_mov_b32_e32 v35, 0
	v_mov_b32_e32 v36, 0
	v_mov_b32_e32 v37, 0
	v_mov_b32_e32 v38, 0
	v_mov_b32_e32 v39, 0
	v_mov_b32_e32 v40, 0
	v_mov_b32_e32 v41, 0
	v_mov_b32_e32 v42, 0
	v_mov_b32_e32 v43, 0
	v_mov_b32_e32 v44, 0
	v_mov_b32_e32 v45, 0
	v_mov_b32_e32 v46, 0
	v_mov_b32_e32 v47, 0
	v_mov_b32_e32 v48, 0
	v_mov_b32_e32 v49, 0
	v_mov_b32_e32 v50, 0
	v_mov_b32_e32 v51, 0
	v_mov_b32_e32 v52, 0
	v_mov_b32_e32 v53, 0
	v_mov_b32_e32 v54, 0
	v_mov_b32_e32 v55, 0
	v_mov_b32_e32 v56, 0
	v_mov_b32_e32 v57, 0
	v_mov_b32_e32 v58, 0
	v_mov_b32_e32 v59, 0
	v_mov_b32_e32 v60, 0
	v_mov_b32_e32 v61, 0
	v_mov_b32_e32 v62, 0
	v_mov_b32_e32 v63, 0
	v_mov_b32_e32 v64, 0
	v_mov_b32_e32 v65, 0
	v_mov_b32_e32 v66, 0
	v_mov_b32_e32 v67, 0
	v_mov_b32_e32 v68, 0
	v_mov_b32_e32 v69, 0
	v_mov_b32_e32 v70, 0
	v_mov_b32_e32 v71, 0
	v_mov_b32_e32 v72, 0
	v_mov_b32_e32 v73, 0
	v_mov_b32_e32 v74, 0
	v_mov_b32_e32 v75, 0
	v_mov_b32_e32 v76, 0
	v_mov_b32_e32 v77, 0
	v_mov_b32_e32 v78, 0
	v_mov_b32_e32 v79, 0
	v_mov_b32_e32 v80, 0
	v_mov_b32_e32 v81, 0
	v_mov_b32_e32 v82, 0
	v_mov_b32_e32 v83, 0
	v_mov_b32_e32 v84, 0
	v_mov_b32_e32 v85, 0
	v_mov_b32_e32 v86, 0
	v_mov_b32_e32 v87, 0
	v_mov_b32_e32 v88, 0
	v_mov_b32_e32 v89, 0
	v_mov_b32_e32 v90, 0
	v_mov_b32_e32 v91, 0
	v_mov_b32_e32 v92, 0
	v_mov_b32_e32 v93, 0
	v_mov_b32_e32 v94, 0
	v_mov_b32_e32 v95, 0
	v_mov_b32_e32 v96, 0
	v_mov_b32_e32 v97, 0
	v_mov_b32_e32 v98, 0
	v_mov_b32_e32 v99, 0
	v_mov_b32_e32 v100, 0
	v_mov_b32_e32 v101, 0
	v_mov_b32_e32 v102, 0
	v_mov_b32_e32 v103, 0
	v_mov_b32_e32 v104, 0
	v_mov_b32_e32 v105, 0
	v_mov_b32_e32 v106, 0
	v_mov_b32_e32 v107, 0
	v_mov_b32_e32 v108, 0
	v_mov_b32_e32 v109, 0
	v_mov_b32_e32 v110, 0
	v_mov_b32_e32 v111, 0
	v_mov_b32_e32 v112, 0
	v_mov_b32_e32 v113, 0
	v_mov_b32_e32 v114, 0
	v_mov_b32_e32 v115, 0
	v_mov_b32_e32 v116, 0
	v_mov_b32_e32 v117, 0
	v_mov_b32_e32 v118, 0
	v_mov_b32_e32 v119, 0
	v_mov_b32_e32 v120, 0
	v_mov_b32_e32 v121, 0
	v_mov_b32_e32 v122, 0
	v_mov_b32_e32 v123, 0
	v_mov_b32_e32 v124, 0
	v_mov_b32_e32 v125, 0
	v_mov_b32_e32 v126, 0
	v_mov_b32_e32 v127, 0
	v_mov_b32_e32 v128, 0
	v_mov_b32_e32 v129, 0
	s_mov_b32 s42, 0
	s_movk_i32 s43, 0x6000
	s_mov_b32 s44, 0xc000
	s_mov_b32 s37, 0
	v_add_u32_e32 v229, v189, v0
	v_add_u32_e32 v228, v189, v188
	s_waitcnt vmcnt(0)
	s_barrier
	ds_read_b128 v[130:133], v228
	ds_read_b128 v[134:137], v228 offset:2048
	ds_read_b128 v[138:141], v228 offset:4096
	ds_read_b128 v[142:145], v228 offset:6144
	ds_read_b128 v[146:149], v229 offset:16384
	ds_read_b128 v[150:153], v229 offset:18432
.Lp5_loop:
	v_add_u32_e32 v230, s42, v190
	v_add_u32_e32 v231, v230, v0
	v_add_u32_e32 v230, v230, v188
	s_waitcnt lgkmcnt(0)
	v_mfma_f32_32x32x16_bf16 v[114:129], v[130:133], v[146:149], v[114:129]
	ds_read_b128 v[174:177], v230
	ds_read_b128 v[170:173], v230 offset:2048
	v_mfma_f32_32x32x16_bf16 v[98:113], v[130:133], v[150:153], v[98:113]
	ds_read_b128 v[162:165], v230 offset:4096
	ds_read_b128 v[154:157], v230 offset:6144
	v_mfma_f32_32x32x16_bf16 v[82:97], v[134:137], v[146:149], v[82:97]
	ds_read_b128 v[166:169], v231 offset:16384
	ds_read_b128 v[158:161], v231 offset:18432
	v_mfma_f32_32x32x16_bf16 v[66:81], v[134:137], v[150:153], v[66:81]
	v_mfma_f32_32x32x16_bf16 v[50:65], v[138:141], v[146:149], v[50:65]
	v_mfma_f32_32x32x16_bf16 v[34:49], v[138:141], v[150:153], v[34:49]
	v_mfma_f32_32x32x16_bf16 v[18:33], v[142:145], v[146:149], v[18:33]
	v_mfma_f32_32x32x16_bf16 v[2:17], v[142:145], v[150:153], v[2:17]
	s_waitcnt vmcnt(0) lgkmcnt(0)
	s_barrier
	v_add_u32_e32 v228, s43, v189
	v_add_u32_e32 v229, v228, v0
	v_add_u32_e32 v228, v228, v188
	v_mfma_f32_32x32x16_bf16 v[114:129], v[174:177], v[166:169], v[114:129]
	ds_read_b128 v[130:133], v228
	ds_read_b128 v[134:137], v228 offset:2048
	v_mfma_f32_32x32x16_bf16 v[98:113], v[174:177], v[158:161], v[98:113]
	ds_read_b128 v[138:141], v228 offset:4096
	ds_read_b128 v[142:145], v228 offset:6144
	v_mfma_f32_32x32x16_bf16 v[82:97], v[170:173], v[166:169], v[82:97]
	ds_read_b128 v[146:149], v229 offset:16384
	ds_read_b128 v[150:153], v229 offset:18432
	s_add_u32 s45, s50, s44
	s_add_u32 s46, s50, s42
	s_add_u32 m0, s45, 0x0
	v_mfma_f32_32x32x16_bf16 v[66:81], v[170:173], v[158:161], v[66:81]
	global_load_lds_dwordx4 v224, s[98:99]
	s_add_u32 m0, s46, 0x0
	s_nop 0
	global_load_lds_dwordx4 v224, s[40:41]
	s_add_u32 m0, s45, 0x1000
	v_mfma_f32_32x32x16_bf16 v[50:65], v[162:165], v[166:169], v[50:65]
	global_load_lds_dwordx4 v225, s[98:99]
	s_add_u32 m0, s46, 0x1000
	s_nop 0
	global_load_lds_dwordx4 v225, s[40:41]
	s_add_u32 m0, s45, 0x2000
	v_mfma_f32_32x32x16_bf16 v[34:49], v[162:165], v[158:161], v[34:49]
	global_load_lds_dwordx4 v226, s[98:99]
	s_add_u32 m0, s46, 0x2000
	s_nop 0
	global_load_lds_dwordx4 v226, s[40:41]
	s_add_u32 m0, s45, 0x3000
	v_mfma_f32_32x32x16_bf16 v[18:33], v[154:157], v[166:169], v[18:33]
	global_load_lds_dwordx4 v227, s[98:99]
	s_add_u32 m0, s46, 0x3000
	s_nop 0
	global_load_lds_dwordx4 v227, s[40:41]
	s_add_u32 m0, s45, 0x4000
	v_mfma_f32_32x32x16_bf16 v[2:17], v[154:157], v[158:161], v[2:17]
	global_load_lds_dwordx4 v224, s[100:101]
	s_add_u32 m0, s46, 0x4000
	s_nop 0
	global_load_lds_dwordx4 v224, s[12:13]
	s_add_u32 m0, s45, 0x5000
	s_nop 0
	global_load_lds_dwordx4 v225, s[100:101]
	s_add_u32 m0, s46, 0x5000
	s_nop 0
	global_load_lds_dwordx4 v225, s[12:13]
	s_add_u32 s98, s98, 0x80
	s_addc_u32 s99, s99, 0
	s_add_u32 s100, s100, 0x80
	s_addc_u32 s101, s101, 0
	s_add_u32 s40, s40, 0x80
	s_addc_u32 s41, s41, 0
	s_add_u32 s12, s12, 0x80
	s_addc_u32 s13, s13, 0
	s_mov_b32 s47, s42
	s_mov_b32 s42, s43
	s_mov_b32 s43, s44
	s_mov_b32 s44, s47
	v_add_u32_e32 v230, s42, v190
	v_add_u32_e32 v231, v230, v0
	v_add_u32_e32 v230, v230, v188
	s_waitcnt lgkmcnt(0)
	v_mfma_f32_32x32x16_bf16 v[114:129], v[130:133], v[146:149], v[114:129]
	ds_read_b128 v[174:177], v230
	ds_read_b128 v[170:173], v230 offset:2048
	v_mfma_f32_32x32x16_bf16 v[98:113], v[130:133], v[150:153], v[98:113]
	ds_read_b128 v[162:165], v230 offset:4096
	ds_read_b128 v[154:157], v230 offset:6144
	v_mfma_f32_32x32x16_bf16 v[82:97], v[134:137], v[146:149], v[82:97]
	ds_read_b128 v[166:169], v231 offset:16384
	ds_read_b128 v[158:161], v231 offset:18432
	v_mfma_f32_32x32x16_bf16 v[66:81], v[134:137], v[150:153], v[66:81]
	v_mfma_f32_32x32x16_bf16 v[50:65], v[138:141], v[146:149], v[50:65]
	v_mfma_f32_32x32x16_bf16 v[34:49], v[138:141], v[150:153], v[34:49]
	v_mfma_f32_32x32x16_bf16 v[18:33], v[142:145], v[146:149], v[18:33]
	v_mfma_f32_32x32x16_bf16 v[2:17], v[142:145], v[150:153], v[2:17]
	s_waitcnt vmcnt(1) lgkmcnt(0)
	s_barrier
	v_add_u32_e32 v228, s43, v189
	v_add_u32_e32 v229, v228, v0
	v_add_u32_e32 v228, v228, v188
	v_mfma_f32_32x32x16_bf16 v[114:129], v[174:177], v[166:169], v[114:129]
	ds_read_b128 v[130:133], v228
	ds_read_b128 v[134:137], v228 offset:2048
	v_mfma_f32_32x32x16_bf16 v[98:113], v[174:177], v[158:161], v[98:113]
	ds_read_b128 v[138:141], v228 offset:4096
	ds_read_b128 v[142:145], v228 offset:6144
	v_mfma_f32_32x32x16_bf16 v[82:97], v[170:173], v[166:169], v[82:97]
	ds_read_b128 v[146:149], v229 offset:16384
	ds_read_b128 v[150:153], v229 offset:18432
	v_mfma_f32_32x32x16_bf16 v[66:81], v[170:173], v[158:161], v[66:81]
	v_mfma_f32_32x32x16_bf16 v[50:65], v[162:165], v[166:169], v[50:65]
	v_mfma_f32_32x32x16_bf16 v[34:49], v[162:165], v[158:161], v[34:49]
	v_mfma_f32_32x32x16_bf16 v[18:33], v[154:157], v[166:169], v[18:33]
	v_mfma_f32_32x32x16_bf16 v[2:17], v[154:157], v[158:161], v[2:17]
	s_mov_b32 s47, s42
	s_mov_b32 s42, s43
	s_mov_b32 s43, s44
	s_mov_b32 s44, s47
	s_add_i32 s37, s37, 1
	s_cmp_lt_u32 s37, 15
	s_cbranch_scc1 .Lp5_loop
	v_add_u32_e32 v230, s42, v190
	v_add_u32_e32 v231, v230, v0
	v_add_u32_e32 v230, v230, v188
	s_waitcnt lgkmcnt(0)
	v_mfma_f32_32x32x16_bf16 v[114:129], v[130:133], v[146:149], v[114:129]
	ds_read_b128 v[174:177], v230
	ds_read_b128 v[170:173], v230 offset:2048
	v_mfma_f32_32x32x16_bf16 v[98:113], v[130:133], v[150:153], v[98:113]
	ds_read_b128 v[162:165], v230 offset:4096
	ds_read_b128 v[154:157], v230 offset:6144
	v_mfma_f32_32x32x16_bf16 v[82:97], v[134:137], v[146:149], v[82:97]
	ds_read_b128 v[166:169], v231 offset:16384
	ds_read_b128 v[158:161], v231 offset:18432
	v_mfma_f32_32x32x16_bf16 v[66:81], v[134:137], v[150:153], v[66:81]
	v_mfma_f32_32x32x16_bf16 v[50:65], v[138:141], v[146:149], v[50:65]
	v_mfma_f32_32x32x16_bf16 v[34:49], v[138:141], v[150:153], v[34:49]
	v_mfma_f32_32x32x16_bf16 v[18:33], v[142:145], v[146:149], v[18:33]
	v_mfma_f32_32x32x16_bf16 v[2:17], v[142:145], v[150:153], v[2:17]
	s_waitcnt vmcnt(0) lgkmcnt(0)
	s_barrier
	v_add_u32_e32 v228, s43, v189
	v_add_u32_e32 v229, v228, v0
	v_add_u32_e32 v228, v228, v188
	v_mfma_f32_32x32x16_bf16 v[114:129], v[174:177], v[166:169], v[114:129]
	ds_read_b128 v[130:133], v228
	ds_read_b128 v[134:137], v228 offset:2048
	v_mfma_f32_32x32x16_bf16 v[98:113], v[174:177], v[158:161], v[98:113]
	ds_read_b128 v[138:141], v228 offset:4096
	ds_read_b128 v[142:145], v228 offset:6144
	v_mfma_f32_32x32x16_bf16 v[82:97], v[170:173], v[166:169], v[82:97]
	ds_read_b128 v[146:149], v229 offset:16384
	ds_read_b128 v[150:153], v229 offset:18432
	v_mfma_f32_32x32x16_bf16 v[66:81], v[170:173], v[158:161], v[66:81]
	v_mfma_f32_32x32x16_bf16 v[50:65], v[162:165], v[166:169], v[50:65]
	v_mfma_f32_32x32x16_bf16 v[34:49], v[162:165], v[158:161], v[34:49]
	v_mfma_f32_32x32x16_bf16 v[18:33], v[154:157], v[166:169], v[18:33]
	v_mfma_f32_32x32x16_bf16 v[2:17], v[154:157], v[158:161], v[2:17]
	s_mov_b32 s47, s42
	s_mov_b32 s42, s43
	s_mov_b32 s43, s44
	s_mov_b32 s44, s47
	v_add_u32_e32 v230, s42, v190
	v_add_u32_e32 v231, v230, v0
	v_add_u32_e32 v230, v230, v188
	s_waitcnt lgkmcnt(0)
	v_mfma_f32_32x32x16_bf16 v[114:129], v[130:133], v[146:149], v[114:129]
	ds_read_b128 v[174:177], v230
	ds_read_b128 v[170:173], v230 offset:2048
	v_mfma_f32_32x32x16_bf16 v[98:113], v[130:133], v[150:153], v[98:113]
	ds_read_b128 v[162:165], v230 offset:4096
	ds_read_b128 v[154:157], v230 offset:6144
	v_mfma_f32_32x32x16_bf16 v[82:97], v[134:137], v[146:149], v[82:97]
	ds_read_b128 v[166:169], v231 offset:16384
	ds_read_b128 v[158:161], v231 offset:18432
	v_mfma_f32_32x32x16_bf16 v[66:81], v[134:137], v[150:153], v[66:81]
	v_mfma_f32_32x32x16_bf16 v[50:65], v[138:141], v[146:149], v[50:65]
	v_mfma_f32_32x32x16_bf16 v[34:49], v[138:141], v[150:153], v[34:49]
	v_mfma_f32_32x32x16_bf16 v[18:33], v[142:145], v[146:149], v[18:33]
	v_mfma_f32_32x32x16_bf16 v[2:17], v[142:145], v[150:153], v[2:17]
	s_waitcnt lgkmcnt(0)
	v_mfma_f32_32x32x16_bf16 v[114:129], v[174:177], v[166:169], v[114:129]
	v_mfma_f32_32x32x16_bf16 v[98:113], v[174:177], v[158:161], v[98:113]
	v_mfma_f32_32x32x16_bf16 v[82:97], v[170:173], v[166:169], v[82:97]
	v_mfma_f32_32x32x16_bf16 v[66:81], v[170:173], v[158:161], v[66:81]
	v_mfma_f32_32x32x16_bf16 v[50:65], v[162:165], v[166:169], v[50:65]
	v_mfma_f32_32x32x16_bf16 v[34:49], v[162:165], v[158:161], v[34:49]
	v_mfma_f32_32x32x16_bf16 v[18:33], v[154:157], v[166:169], v[18:33]
	v_mfma_f32_32x32x16_bf16 v[2:17], v[154:157], v[158:161], v[2:17]
	s_branch .LBB0_993
